# stack C + final-iteration tile prefetches skipped in the cmp/sel/win loops (no exposed wait for useless clamped loads after each loop)
# baseline (speedup 1.0000x reference)
.LBB0_1018:
	v_mul_f32_e32 v33, 0.5, v67
	ds_bpermute_b32 v33, v181, v33
	v_add_f32_e32 v35, v64, v65
	v_fma_f32 v36, 0.5, v67, v66
	v_add_f32_e32 v35, v35, v36
	v_add_u32_e32 v34, 0x13f80, v91
	s_waitcnt lgkmcnt(0)
	v_cndmask_b32_e64 v36, v33, v81, s[4:5]
	v_add_f32_e32 v35, v36, v35
	v_mul_f32_e32 v36, 0.5, v71
	ds_bpermute_b32 v36, v181, v36
	ds_write_b32 v34, v35
	v_add_f32_e32 v34, v68, v69
	v_fma_f32 v35, 0.5, v71, v70
	v_add_f32_e32 v34, v34, v35
	v_mul_f32_e32 v35, 0.5, v75
	ds_bpermute_b32 v35, v181, v35
	s_waitcnt lgkmcnt(2)
	v_cndmask_b32_e64 v33, v36, v33, s[4:5]
	v_add_f32_e32 v33, v34, v33
	v_add_u32_e32 v34, 0x13f90, v91
	ds_write_b32 v34, v33
	v_add_f32_e32 v33, v72, v73
	v_fma_f32 v34, 0.5, v75, v74
	v_add_f32_e32 v33, v33, v34
	s_waitcnt lgkmcnt(1)
	v_cndmask_b32_e64 v34, v35, v36, s[4:5]
	v_mul_f32_e32 v36, 0.5, v79
	ds_bpermute_b32 v81, v181, v36
	v_add_f32_e32 v33, v33, v34
	v_add_u32_e32 v34, 0x13fa0, v91
	ds_write_b32 v34, v33
	v_add_f32_e32 v33, v76, v77
	v_fma_f32 v34, 0.5, v79, v78
	v_add_f32_e32 v33, v33, v34
	s_waitcnt lgkmcnt(1)
	v_cndmask_b32_e64 v34, v81, v35, s[4:5]
	v_add_f32_e32 v33, v33, v34
	v_add_u32_e32 v34, 0x13fb0, v91
	v_add_f32_e32 v32, v80, v90
	ds_write_b32 v34, v33
	v_add_f32_e32 v80, v32, v107
	ds_read_b128 v[32:35], v92 offset:40960
	ds_read_b128 v[36:39], v92 offset:43520
	ds_read_b128 v[40:43], v92 offset:46080
	ds_read_b128 v[94:97], v92 offset:48640
	v_cvt_pk_bf16_f32 v64, v64, v65
	v_cvt_pk_bf16_f32 v65, v66, v67
	v_cvt_pk_bf16_f32 v66, v68, v69
	v_cvt_pk_bf16_f32 v67, v70, v71
	s_setprio 1
	s_waitcnt lgkmcnt(3)
	v_mfma_f32_16x16x32_bf16 v[16:19], v[32:35], v[64:67], v[16:19]
	s_waitcnt lgkmcnt(2)
	v_mfma_f32_16x16x32_bf16 v[20:23], v[36:39], v[64:67], v[20:23]
	s_waitcnt lgkmcnt(1)
	v_mfma_f32_16x16x32_bf16 v[24:27], v[40:43], v[64:67], v[24:27]
	s_waitcnt lgkmcnt(0)
	v_mfma_f32_16x16x32_bf16 v[28:31], v[94:97], v[64:67], v[28:31]
	s_setprio 0
	ds_read_b128 v[32:35], v92 offset:41024
	ds_read_b128 v[36:39], v92 offset:43584
	ds_read_b128 v[40:43], v92 offset:46144
	ds_read_b128 v[64:67], v92 offset:48704
	v_cvt_pk_bf16_f32 v90, v72, v73
	v_cvt_pk_bf16_f32 v91, v74, v75
	v_cvt_pk_bf16_f32 v92, v76, v77
	v_cvt_pk_bf16_f32 v93, v78, v79
	s_setprio 1
	s_waitcnt lgkmcnt(3)
	v_mfma_f32_16x16x32_bf16 v[72:75], v[32:35], v[90:93], v[16:19]
	s_waitcnt lgkmcnt(2)
	v_mfma_f32_16x16x32_bf16 v[76:79], v[36:39], v[90:93], v[20:23]
	s_waitcnt lgkmcnt(1)
	v_mfma_f32_16x16x32_bf16 v[68:71], v[40:43], v[90:93], v[24:27]
	s_waitcnt lgkmcnt(0)
	v_mfma_f32_16x16x32_bf16 v[64:67], v[64:67], v[90:93], v[28:31]
	s_setprio 0
	s_sub_i32 s0, s23, 64
	s_and_b32 s0, s0, 0x80
	s_mulk_i32 s0, 0xa0
	v_add_u32_e32 v16, s0, v151
	s_waitcnt vmcnt(3)
	ds_write_b128 v16, v[4:7]
	v_add_u32_e32 v4, s0, v152
	s_and_b32 s0, s23, 0xc0
	v_add_u32_e32 v4, 0xa000, v4
	s_mulk_i32 s0, 0xa0
	s_waitcnt vmcnt(2)
	ds_write2_b64 v4, v[0:1], v[2:3] offset1:2
	v_add_u32_e32 v0, s0, v151
	s_waitcnt vmcnt(1)
	ds_write_b128 v0, v[12:15]
	v_add_u32_e32 v0, s0, v152
	s_add_i32 s0, s24, -1
	s_min_i32 s0, s0, s21
	s_lshl_b32 s0, s0, 6
	s_ashr_i32 s1, s0, 31
	s_lshl_b64 s[26:27], s[0:1], 7
	v_lshl_add_u64 v[2:3], s[0:1], 1, v[46:47]
	s_min_i32 s0, s24, s21
	s_lshl_b32 s0, s0, 6
	v_add_u32_e32 v0, 0xa000, v0
	s_ashr_i32 s1, s0, 31
	s_waitcnt vmcnt(0)
	ds_write2_b64 v0, v[8:9], v[10:11] offset1:2
	s_add_i32 s98, s24, -1
	s_cmp_gt_i32 s98, s21
	s_cbranch_scc1 .Lcmp_skip_pf
	v_lshl_add_u64 v[0:1], v[44:45], 0, s[26:27]
	s_lshl_b64 s[26:27], s[0:1], 7
	global_load_dwordx4 v[4:7], v[0:1], off
	s_nop 0
	global_load_dwordx4 v[0:3], v[2:3], off
	v_lshl_add_u64 v[8:9], v[44:45], 0, s[26:27]
	v_lshl_add_u64 v[10:11], s[0:1], 1, v[46:47]
	global_load_dwordx4 v[12:15], v[8:9], off
	s_nop 0
	global_load_dwordx4 v[8:11], v[10:11], off
.Lcmp_skip_pf:
	s_waitcnt lgkmcnt(0)
	s_barrier
	s_add_i32 s0, s24, 2
	s_add_i32 s1, s24, -2
	s_addk_i32 s23, 0x80
	s_cmp_lt_i32 s1, s20
	v_add_u32_e32 v89, 0xfffff800, v89
	s_cbranch_scc0 .LBB0_1020
	s_mov_b32 s24, s0
	s_branch .LBB0_1010

.LBB0_1048:
	s_setprio 0
	s_add_i32 s0, s83, -1
	s_cmp_lt_u32 s0, s79
	s_cselect_b32 s0, s0, s80
	s_lshl_b32 s0, s0, 2
	s_add_i32 s0, s0, 0x24900
	v_mov_b32_e32 v33, s0
	ds_read_b32 v33, v33
	s_cmp_lt_u32 s83, s79
	s_cselect_b32 s0, s83, s80
	s_lshl_b32 s0, s0, 2
	s_add_i32 s0, s0, 0x24900
	v_mov_b32_e32 v34, s0
	ds_read_b32 v34, v34
	s_and_b32 s0, s81, 0x80
	s_mulk_i32 s0, 0xa0
	v_add_u32_e32 v32, s0, v151
	s_waitcnt vmcnt(3)
	ds_write_b128 v32, v[20:23]
	v_add_u32_e32 v20, s0, v152
	s_add_i32 s0, s81, 64
	s_and_b32 s0, s0, 0xc0
	v_add_u32_e32 v20, 0xa000, v20
	s_mulk_i32 s0, 0xa0
	s_waitcnt vmcnt(2)
	ds_write2_b64 v20, v[16:17], v[18:19] offset1:2
	v_add_u32_e32 v16, s0, v151
	s_waitcnt vmcnt(1)
	ds_write_b128 v16, v[28:31]
	v_add_u32_e32 v16, s0, v152
	s_add_i32 s0, s83, -1
	s_cmp_lt_u32 s0, s79
	s_cselect_b32 s0, s0, s80
	s_lshl_b32 s0, s0, 2
	s_add_i32 s22, 0, 0x24900
	v_add_u32_e32 v16, 0xa000, v16
	s_add_i32 s0, s22, s0
	s_waitcnt vmcnt(0)
	ds_write2_b64 v16, v[24:25], v[26:27] offset1:2
	s_waitcnt lgkmcnt(4)
	v_readfirstlane_b32 s98, v33
	v_readfirstlane_b32 s99, v34
	s_addk_i32 s81, 0x80
	s_add_i32 s82, s82, 8
	s_add_i32 s1, s83, -1
	s_cmp_ge_u32 s1, s79
	s_cbranch_scc1 .Lsel_skip_pf
	s_lshl_b32 s0, s98, 6
	s_ashr_i32 s1, s0, 31
	s_lshl_b64 s[20:21], s[0:1], 12
	v_lshl_add_u64 v[18:19], s[0:1], 1, v[148:149]
	v_lshl_add_u64 v[16:17], v[120:121], 0, s[20:21]
	global_load_dwordx4 v[20:23], v[16:17], off offset:2560
	s_nop 0
	global_load_dwordx4 v[16:19], v[18:19], off
	s_lshl_b32 s0, s99, 6
	s_ashr_i32 s1, s0, 31
	s_lshl_b64 s[20:21], s[0:1], 12
	v_lshl_add_u64 v[24:25], v[120:121], 0, s[20:21]
	v_lshl_add_u64 v[26:27], s[0:1], 1, v[148:149]
	global_load_dwordx4 v[28:31], v[24:25], off offset:2560
	s_nop 0
	global_load_dwordx4 v[24:27], v[26:27], off
.Lsel_skip_pf:
	s_waitcnt lgkmcnt(0)
	s_barrier
	s_mov_b32 s32, s89
	s_mov_b32 s97, s91
	s_mov_b32 s89, s98
	s_mov_b32 s91, s99
	s_add_i32 s0, s83, 2
	s_add_i32 s1, s83, -2
	s_cmp_lt_u32 s1, s79
	s_cbranch_scc0 .LBB0_1051
	v_mov_b64_e32 v[32:33], v[80:81]
	s_mov_b32 s83, s0
	v_mov_b64_e32 v[34:35], v[82:83]
	v_mov_b32_e32 v36, v0
	v_mov_b32_e32 v37, v1
	v_mov_b32_e32 v38, v2
	v_mov_b32_e32 v39, v3
	v_mov_b32_e32 v40, v4
	v_mov_b32_e32 v41, v5
	v_mov_b32_e32 v42, v6
	v_mov_b32_e32 v43, v7
	v_mov_b32_e32 v44, v8
	v_mov_b32_e32 v45, v9
	v_mov_b32_e32 v46, v10
	v_mov_b32_e32 v47, v11
	v_mov_b32_e32 v84, v12
	v_mov_b32_e32 v85, v13
	v_mov_b32_e32 v86, v14
	v_mov_b32_e32 v87, v15
	s_branch .LBB0_1040

.LBB0_1066:
	s_setprio 0
	s_add_i32 s0, s24, 0x80
	s_and_b32 s1, s0, 0x80
	s_mulk_i32 s1, 0xa0
	v_add_u32_e32 v86, s1, v151
	s_waitcnt vmcnt(3)
	ds_write_b128 v86, v[36:39]
	v_add_u32_e32 v36, s1, v152
	s_add_i32 s1, s24, 0xc0
	s_and_b32 s1, s1, 0xc0
	v_add_u32_e32 v36, 0xa000, v36
	s_mulk_i32 s1, 0xa0
	s_waitcnt vmcnt(2)
	ds_write2_b64 v36, v[32:33], v[34:35] offset1:2
	v_add_u32_e32 v32, s1, v151
	s_waitcnt vmcnt(1)
	ds_write_b128 v32, v[44:47]
	v_add_u32_e32 v32, s1, v152
	s_add_i32 s1, s23, -1
	s_min_i32 s1, s1, s21
	s_lshl_b32 s1, s1, 6
	s_add_i32 s24, s1, s20
	s_min_i32 s1, s23, s21
	s_ashr_i32 s25, s24, 31
	s_lshl_b32 s1, s1, 6
	s_lshl_b64 s[26:27], s[24:25], 12
	v_lshl_add_u64 v[34:35], s[24:25], 1, v[106:107]
	s_add_i32 s24, s1, s20
	v_add_u32_e32 v32, 0xa000, v32
	s_ashr_i32 s25, s24, 31
	s_waitcnt vmcnt(0)
	ds_write2_b64 v32, v[40:41], v[42:43] offset1:2
	s_add_i32 s98, s23, -1
	s_cmp_gt_i32 s98, s21
	s_cbranch_scc1 .Lwin_skip_pf
	v_lshl_add_u64 v[32:33], v[120:121], 0, s[26:27]
	s_lshl_b64 s[26:27], s[24:25], 12
	global_load_dwordx4 v[36:39], v[32:33], off offset:3072
	s_nop 0
	global_load_dwordx4 v[32:35], v[34:35], off
	v_lshl_add_u64 v[40:41], v[120:121], 0, s[26:27]
	v_lshl_add_u64 v[42:43], s[24:25], 1, v[106:107]
	global_load_dwordx4 v[44:47], v[40:41], off offset:3072
	s_nop 0
	global_load_dwordx4 v[40:43], v[42:43], off
.Lwin_skip_pf:
	s_waitcnt lgkmcnt(0)
	s_barrier
	s_add_i32 s1, s23, 2
	s_add_i32 s23, s23, -3
	s_cmp_lt_i32 s23, s21
	v_add_u32_e32 v81, 0xffffff80, v81
	s_cbranch_scc0 .LBB0_1069
	v_mov_b64_e32 v[88:89], v[84:85]
	s_mov_b32 s24, s0
	s_mov_b32 s23, s1
	v_mov_b64_e32 v[86:87], v[82:83]
	v_mov_b32_e32 v90, v16
	v_mov_b32_e32 v91, v17
	v_mov_b32_e32 v92, v18
	v_mov_b32_e32 v93, v19
	v_mov_b32_e32 v94, v20
	v_mov_b32_e32 v95, v21
	v_mov_b32_e32 v96, v22
	v_mov_b32_e32 v97, v23
	v_mov_b32_e32 v98, v24
	v_mov_b32_e32 v99, v25
	v_mov_b32_e32 v100, v26
	v_mov_b32_e32 v101, v27
	v_mov_b32_e32 v102, v28
	v_mov_b32_e32 v103, v29
	v_mov_b32_e32 v104, v30
	v_mov_b32_e32 v105, v31
	s_branch .LBB0_1061
